# lnffn: rows after a wave's first are claimed from a per-workgroup LDS counter (waves with many expert rows take fewer rows)
# speedup vs baseline: 1.0038x; 1.0038x over previous
.LBB0_991:
	s_cmp_lt_i32 s91, 11
	s_cbranch_scc1 .LBB0_1045
	s_waitcnt vmcnt(0)
	s_waitcnt vmcnt(0) lgkmcnt(0)
	s_barrier
	s_mov_b64 s[4:5], exec
	v_readlane_b32 s0, v126, 10
	v_readlane_b32 s1, v126, 11
	s_and_b64 s[0:1], s[4:5], s[0:1]
	s_mov_b64 exec, s[0:1]
	s_cbranch_execz .LBB0_1044
	v_readlane_b32 s8, v126, 12
	v_readlane_b32 s9, v126, 13
	v_readlane_b32 s3, v126, 14
	v_mov_b32_e32 v0, 0
	v_mov_b32_e32 v1, 1
	v_mov_b32_e32 v5, 0x23fe0
	ds_write_b32 v5, v0
	s_lshl_b32 s3, s3, 8
	s_add_u32 s0, s8, s3
	s_addc_u32 s1, s9, 0
	s_add_u32 s0, s0, 0x1400
	s_addc_u32 s1, s1, 0
	global_atomic_add v4, v0, v1, s[0:1] sc0
	buffer_inv sc1
	v_mov_b32_e32 v5, 0x23ff0
	ds_read2_b32 v[2:3], v5 offset1:1
	s_add_u32 s8, s8, 0x2400
	s_addc_u32 s9, s9, 0
	s_sub_i32 s1, 10, s90
	s_mov_b32 s7, 0
	s_waitcnt lgkmcnt(0)
	v_readfirstlane_b32 s0, v2
	v_readfirstlane_b32 s6, v3
	s_mul_i32 s0, s0, s1
	s_mul_i32 s6, s6, s1
	s_waitcnt vmcnt(1)
	v_readfirstlane_b32 s1, v4
	s_add_i32 s1, s1, 1
	s_cmp_lg_u32 s1, s0
	s_cbranch_scc1 .Lgb9_poll0
	buffer_wbl2 sc1
	s_waitcnt vmcnt(0)
	global_atomic_add v0, v1, s[8:9]
	global_atomic_add v0, v1, s[8:9] offset:256
	global_atomic_add v0, v1, s[8:9] offset:512
	global_atomic_add v0, v1, s[8:9] offset:768
	global_atomic_add v0, v1, s[8:9] offset:1024
	global_atomic_add v0, v1, s[8:9] offset:1280
	global_atomic_add v0, v1, s[8:9] offset:1536
	global_atomic_add v0, v1, s[8:9] offset:1792
	global_atomic_add v0, v1, s[8:9] offset:2048
	global_atomic_add v0, v1, s[8:9] offset:2304
	global_atomic_add v0, v1, s[8:9] offset:2560
	global_atomic_add v0, v1, s[8:9] offset:2816
	global_atomic_add v0, v1, s[8:9] offset:3072
	global_atomic_add v0, v1, s[8:9] offset:3328
	global_atomic_add v0, v1, s[8:9] offset:3584
	global_atomic_add v0, v1, s[8:9] offset:3840

.LBB0_1045:
	s_cmp_lt_i32 s90, 11
	s_cselect_b64 s[0:1], -1, 0
	s_cmp_gt_i32 s91, 10
	s_cselect_b64 s[4:5], -1, 0
	s_and_b64 s[0:1], s[0:1], s[4:5]
	s_andn2_b64 vcc, exec, s[0:1]
	s_cbranch_vccnz .LBB0_1109
	s_mov_b32 s32, 0
	s_waitcnt lgkmcnt(0)
	s_load_dword s3, s[96:97], 0x128
	s_waitcnt vmcnt(0)
	v_mov_b32_e32 v2, v77
	s_add_u32 s6, s96, 0x128
	v_ashrrev_i32_e32 v0, 6, v2
	v_lshl_add_u32 v22, s2, 3, v0
	s_movk_i32 s17, 0x4000
	s_addc_u32 s7, s97, 0
	v_cmp_gt_i32_e32 vcc, s17, v22
	s_and_saveexec_b64 s[8:9], vcc
	s_cbranch_execz .LBB0_1055
	v_readlane_b32 s36, v126, 2
	v_readlane_b32 s42, v126, 8
	v_readlane_b32 s43, v126, 9
	s_add_u32 s4, s42, 0x1d3e8000
	s_addc_u32 s5, s43, 0
	s_waitcnt lgkmcnt(0)
	s_lshl_b32 s24, s3, 3
	s_add_u32 s0, s42, 0x190c8000
	v_ashrrev_i32_e32 v23, 31, v22
	s_addc_u32 s1, s43, 0
	v_and_b32_e32 v3, 15, v2
	v_lshlrev_b64 v[0:1], 6, v[22:23]
	v_lshl_add_u64 v[4:5], s[0:1], 0, v[0:1]
	v_lshlrev_b32_e32 v0, 2, v3
	v_mov_b32_e32 v1, 0
	v_lshlrev_b32_e32 v2, 2, v2
	v_lshl_add_u64 v[6:7], v[4:5], 0, v[0:1]
	v_lshlrev_b64 v[4:5], 11, v[22:23]
	v_and_b32_e32 v20, 0xfc, v2
	v_lshl_add_u64 v[4:5], s[4:5], 0, v[4:5]
	v_lshlrev_b32_e32 v8, 1, v20
	v_mov_b32_e32 v9, v1
	v_lshl_add_u64 v[2:3], v[4:5], 0, v[8:9]
	global_load_dwordx2 v[30:31], v[2:3], off
	global_load_dwordx2 v[28:29], v[2:3], off offset:512
	global_load_dwordx2 v[26:27], v[2:3], off offset:1024
	global_load_dwordx2 v[24:25], v[2:3], off offset:1536
	global_load_dword v5, v[6:7], off
	v_mbcnt_lo_u32_b32 v2, -1, 0
	v_mbcnt_hi_u32_b32 v7, -1, v2
	v_and_b32_e32 v11, 64, v7
	v_xor_b32_e32 v16, 1, v7
	v_lshl_add_u64 v[2:3], s[4:5], 0, v[8:9]
	v_lshl_add_u64 v[14:15], s[42:43], 0, v[8:9]
	v_add_u32_e32 v9, 64, v11
	v_xor_b32_e32 v17, 2, v7
	v_or_b32_e32 v10, 0x300, v20
	v_cmp_lt_i32_e32 vcc, v16, v9
	v_xor_b32_e32 v18, 4, v7
	v_lshlrev_b32_e32 v8, 2, v10
	v_lshl_add_u64 v[10:11], s[0:1], 0, v[0:1]
	v_cndmask_b32_e32 v0, v7, v16, vcc
	v_cmp_lt_i32_e32 vcc, v17, v9
	v_xor_b32_e32 v19, 8, v7
	v_xor_b32_e32 v21, 16, v7
	v_cndmask_b32_e32 v16, v7, v17, vcc
	v_cmp_lt_i32_e32 vcc, v18, v9
	v_xor_b32_e32 v23, 32, v7
	s_mov_b64 s[22:23], 0x333e8000
	v_cndmask_b32_e32 v17, v7, v18, vcc
	v_cmp_lt_i32_e32 vcc, v19, v9
	s_mov_b64 s[30:31], 0x193e8000
	v_or_b32_e32 v4, 0x100, v20
	v_cndmask_b32_e32 v18, v7, v19, vcc
	v_cmp_lt_i32_e32 vcc, v21, v9
	v_or_b32_e32 v6, 0x200, v20
	s_add_u32 s20, s42, 0x18e80000
	v_cndmask_b32_e32 v19, v7, v21, vcc
	v_cmp_lt_i32_e32 vcc, v23, v9
	v_lshlrev_b32_e32 v55, 2, v0
	v_lshlrev_b32_e32 v0, 2, v20
	v_cndmask_b32_e32 v7, v7, v23, vcc
	s_mov_b32 s11, 0
	s_mov_b64 s[12:13], 0
	s_movk_i32 s25, 0x3fff
	s_movk_i32 s26, 0x1fff
	s_movk_i32 s27, 0x6000
	s_mov_b64 s[14:15], 0x5000
	s_mov_b32 s16, 0x3fb504f3
	v_mov_b32_e32 v54, 0x358637bd
	s_mov_b32 s28, 0x800000
	s_mov_b64 s[18:19], 0x1000
	v_lshlrev_b32_e32 v4, 2, v4
	v_lshlrev_b32_e32 v6, 2, v6
	v_lshl_add_u64 v[12:13], v[14:15], 0, s[22:23]
	v_lshl_add_u64 v[14:15], v[14:15], 0, s[30:31]
	s_addc_u32 s21, s43, 0
	v_lshlrev_b32_e32 v56, 2, v16
	v_lshlrev_b32_e32 v57, 2, v17
	v_lshlrev_b32_e32 v58, 2, v18
	v_lshlrev_b32_e32 v59, 2, v19
	v_lshlrev_b32_e32 v60, 2, v7
	v_lshl_add_u64 v[16:17], s[54:55], 0, v[0:1]
	v_lshl_add_u64 v[18:19], s[56:57], 0, v[0:1]
	v_lshlrev_b32_e32 v0, 2, v20
	v_readlane_b32 s37, v126, 3
	v_readlane_b32 s38, v126, 4
	v_readlane_b32 s39, v126, 5
	v_readlane_b32 s40, v126, 6
	v_readlane_b32 s41, v126, 7
	s_waitcnt vmcnt(4)
	v_mov_b64_e32 v[62:63], v[30:31]
	s_waitcnt vmcnt(3)
	v_mov_b64_e32 v[64:65], v[28:29]
	s_waitcnt vmcnt(2)
	v_mov_b64_e32 v[66:67], v[26:27]
	s_waitcnt vmcnt(1)
	v_mov_b64_e32 v[68:69], v[24:25]
	s_waitcnt vmcnt(0)
	v_mov_b32_e32 v61, v5
	global_load_dwordx4 a[8:11], v[16:17], off
	global_load_dwordx4 a[12:15], v[18:19], off
	global_load_dwordx4 a[16:19], v[16:17], off offset:1024
	global_load_dwordx4 a[20:23], v[18:19], off offset:1024
	global_load_dwordx4 a[24:27], v[16:17], off offset:2048
	global_load_dwordx4 a[28:31], v[18:19], off offset:2048
	global_load_dwordx4 a[32:35], v[16:17], off offset:3072
	global_load_dwordx4 a[36:39], v[18:19], off offset:3072
	s_branch .LBB0_1050

.LBB0_1050:
	v_readfirstlane_b32 s58, v22
	s_sub_i32 s59, s58, 0x2000
	s_ashr_i32 s59, s59, 11
	s_add_i32 s59, s59, 1
	s_cmp_lt_i32 s58, 0x2000
	s_cselect_b32 s59, 0, s59
	s_mul_i32 s59, s59, 0x6000
	s_add_u32 s60, s20, s59
	s_addc_u32 s61, s21, 0
	s_add_u32 s62, s60, 0x1e000
	s_addc_u32 s63, s61, 0
	s_add_u32 s58, s60, 0x1f000
	s_addc_u32 s59, s61, 0
	s_add_u32 s60, s60, 0x5000
	s_addc_u32 s61, s61, 0
	global_load_dwordx4 a[40:43], v0, s[60:61]
	global_load_dwordx4 a[44:47], v0, s[60:61] offset:1024
	global_load_dwordx4 a[48:51], v0, s[60:61] offset:2048
	global_load_dwordx4 a[52:55], v0, s[60:61] offset:3072
	global_load_dwordx4 a[56:59], v0, s[58:59]
	global_load_dwordx4 a[72:75], v0, s[62:63]
	global_load_dwordx4 a[60:63], v0, s[58:59] offset:1024
	global_load_dwordx4 a[76:79], v0, s[62:63] offset:1024
	global_load_dwordx4 a[64:67], v0, s[58:59] offset:2048
	global_load_dwordx4 a[80:83], v0, s[62:63] offset:2048
	global_load_dwordx4 a[68:71], v0, s[58:59] offset:3072
	global_load_dwordx4 a[84:87], v0, s[62:63] offset:3072
	s_nop 1
	v_mbcnt_lo_u32_b32 v32, -1, 0
	v_mbcnt_hi_u32_b32 v32, -1, v32
	v_cmp_eq_u32_e32 vcc, 0, v32
	s_nop 1
	v_cndmask_b32_e64 v33, 0, 1, vcc
	v_mov_b32_e32 v32, 0x23fe0
	ds_add_rtn_u32 v20, v32, v33
	s_waitcnt lgkmcnt(0)
	v_readfirstlane_b32 s30, v20
	s_and_b32 s31, s30, 7
	s_lshr_b32 s30, s30, 3
	s_add_i32 s30, s30, 1
	s_lshl_b32 s30, s30, 11
	s_add_i32 s30, s30, s31
	s_lshl_b32 s31, s2, 3
	s_add_i32 s30, s30, s31
	s_add_i32 s32, s32, 1
	s_cmp_gt_u32 s32, 64
	s_cselect_b32 s30, 0x4000, s30
	v_mov_b32_e32 v20, s30
	v_cmp_gt_i32_e64 s[4:5], s17, v20
	v_cmp_lt_i32_e32 vcc, s25, v20
	s_and_saveexec_b64 s[0:1], s[4:5]
	s_cbranch_execz .LBB0_1052
	v_ashrrev_i32_e32 v21, 31, v20
	v_lshlrev_b64 v[32:33], 6, v[20:21]
	v_lshl_add_u64 v[32:33], v[10:11], 0, v[32:33]
	v_lshlrev_b64 v[34:35], 11, v[20:21]
	v_lshl_add_u64 v[34:35], v[2:3], 0, v[34:35]
	global_load_dword v61, v[32:33], off
	global_load_dwordx2 v[62:63], v[34:35], off
	global_load_dwordx2 v[64:65], v[34:35], off offset:512
	global_load_dwordx2 v[66:67], v[34:35], off offset:1024
	global_load_dwordx2 v[68:69], v[34:35], off offset:1536

.LBB0_1592:
	s_cmp_lt_i32 s91, 19
	s_cbranch_scc1 .LBB0_1646
	s_waitcnt vmcnt(0)
	s_waitcnt vmcnt(0) lgkmcnt(0)
	s_barrier
	s_mov_b64 s[4:5], exec
	v_readlane_b32 s0, v126, 10
	v_readlane_b32 s1, v126, 11
	s_and_b64 s[0:1], s[4:5], s[0:1]
	s_mov_b64 exec, s[0:1]
	s_cbranch_execz .LBB0_1645
	v_readlane_b32 s8, v126, 12
	v_readlane_b32 s9, v126, 13
	v_readlane_b32 s3, v126, 14
	v_mov_b32_e32 v0, 0
	v_mov_b32_e32 v1, 1
	v_mov_b32_e32 v5, 0x23fe0
	ds_write_b32 v5, v0
	s_lshl_b32 s3, s3, 8
	s_add_u32 s0, s8, s3
	s_addc_u32 s1, s9, 0
	s_add_u32 s0, s0, 0x1400
	s_addc_u32 s1, s1, 0
	global_atomic_add v4, v0, v1, s[0:1] sc0
	buffer_inv sc1
	v_mov_b32_e32 v5, 0x23ff0
	ds_read2_b32 v[2:3], v5 offset1:1
	s_add_u32 s8, s8, 0x2400
	s_addc_u32 s9, s9, 0
	s_sub_i32 s1, 18, s90
	s_mov_b32 s7, 0
	s_waitcnt lgkmcnt(0)
	v_readfirstlane_b32 s0, v2
	v_readfirstlane_b32 s6, v3
	s_mul_i32 s0, s0, s1
	s_mul_i32 s6, s6, s1
	s_waitcnt vmcnt(1)
	v_readfirstlane_b32 s1, v4
	s_add_i32 s1, s1, 1
	s_cmp_lg_u32 s1, s0
	s_cbranch_scc1 .Lgb17_poll0
	buffer_wbl2 sc1
	s_waitcnt vmcnt(0)
	global_atomic_add v0, v1, s[8:9]
	global_atomic_add v0, v1, s[8:9] offset:256
	global_atomic_add v0, v1, s[8:9] offset:512
	global_atomic_add v0, v1, s[8:9] offset:768
	global_atomic_add v0, v1, s[8:9] offset:1024
	global_atomic_add v0, v1, s[8:9] offset:1280
	global_atomic_add v0, v1, s[8:9] offset:1536
	global_atomic_add v0, v1, s[8:9] offset:1792
	global_atomic_add v0, v1, s[8:9] offset:2048
	global_atomic_add v0, v1, s[8:9] offset:2304
	global_atomic_add v0, v1, s[8:9] offset:2560
	global_atomic_add v0, v1, s[8:9] offset:2816
	global_atomic_add v0, v1, s[8:9] offset:3072
	global_atomic_add v0, v1, s[8:9] offset:3328
	global_atomic_add v0, v1, s[8:9] offset:3584
	global_atomic_add v0, v1, s[8:9] offset:3840

.LBB0_1646:
	s_cmp_lt_i32 s90, 19
	s_cselect_b64 s[0:1], -1, 0
	s_cmp_gt_i32 s91, 18
	s_cselect_b64 s[4:5], -1, 0
	s_and_b64 s[0:1], s[0:1], s[4:5]
	s_andn2_b64 vcc, exec, s[0:1]
	s_cbranch_vccnz .LBB0_1710
	s_mov_b32 s32, 0
	s_lshl_b32 s58, s2, 3
	s_load_dword s13, s[96:97], 0x128
	s_add_u32 s4, s96, 0x128
	v_ashrrev_i32_e32 v0, 6, v77
	s_waitcnt vmcnt(0)
	v_lshl_add_u32 v8, s2, 3, v0
	s_movk_i32 s18, 0x4000
	s_addc_u32 s5, s97, 0
	v_cmp_gt_i32_e32 vcc, s18, v8
	s_waitcnt lgkmcnt(0)
	s_and_saveexec_b64 s[2:3], vcc
	s_cbranch_execz .LBB0_1656
	v_readlane_b32 s20, v126, 2
	v_readlane_b32 s21, v126, 3
	v_readlane_b32 s22, v126, 4
	v_readlane_b32 s23, v126, 5
	v_readlane_b32 s24, v126, 6
	v_readlane_b32 s25, v126, 7
	v_readlane_b32 s26, v126, 8
	v_readlane_b32 s27, v126, 9
	s_mov_b64 s[20:21], s[24:25]
	s_lshl_b32 s19, s13, 3
	s_mov_b64 s[22:23], s[26:27]
	s_add_u32 s6, s22, 0x1d3e8000
	s_addc_u32 s7, s23, 0
	s_add_u32 s0, s56, 0x1000
	s_addc_u32 s1, s57, 0
	s_add_u32 s8, s54, 0x1000
	s_addc_u32 s9, s55, 0
	s_add_u32 s10, s22, 0x190c8000
	v_ashrrev_i32_e32 v9, 31, v8
	s_addc_u32 s11, s23, 0
	v_and_b32_e32 v4, 15, v77
	v_lshlrev_b64 v[0:1], 6, v[8:9]
	v_lshlrev_b32_e32 v6, 2, v77
	v_lshl_add_u64 v[2:3], s[10:11], 0, v[0:1]
	v_lshlrev_b32_e32 v0, 2, v4
	v_mov_b32_e32 v1, 0
	v_lshlrev_b64 v[4:5], 11, v[8:9]
	v_and_b32_e32 v28, 0xfc, v6
	v_lshl_add_u64 v[4:5], s[6:7], 0, v[4:5]
	v_lshlrev_b32_e32 v6, 1, v28
	v_mov_b32_e32 v7, v1
	v_lshl_add_u64 v[4:5], v[4:5], 0, v[6:7]
	v_lshl_add_u64 v[2:3], v[2:3], 0, v[0:1]
	global_load_dwordx2 v[42:43], v[4:5], off
	global_load_dwordx2 v[40:41], v[4:5], off offset:512
	global_load_dwordx2 v[38:39], v[4:5], off offset:1024
	global_load_dwordx2 v[36:37], v[4:5], off offset:1536
	global_load_dword v9, v[2:3], off
	v_lshl_add_u64 v[2:3], s[10:11], 0, v[0:1]
	v_mbcnt_lo_u32_b32 v0, -1, 0
	v_mbcnt_hi_u32_b32 v0, -1, v0
	v_and_b32_e32 v10, 64, v0
	v_add_u32_e32 v10, 64, v10
	v_xor_b32_e32 v11, 1, v0
	v_cmp_lt_i32_e32 vcc, v11, v10
	v_or_b32_e32 v30, 0x100, v28
	v_or_b32_e32 v32, 0x200, v28
	v_cndmask_b32_e32 v11, v0, v11, vcc
	v_lshlrev_b32_e32 v61, 2, v11
	v_xor_b32_e32 v11, 2, v0
	v_cmp_lt_i32_e32 vcc, v11, v10
	v_or_b32_e32 v34, 0x300, v28
	v_lshl_add_u64 v[4:5], s[6:7], 0, v[6:7]
	v_cndmask_b32_e32 v11, v0, v11, vcc
	v_lshlrev_b32_e32 v66, 2, v11
	v_xor_b32_e32 v11, 4, v0
	v_cmp_lt_i32_e32 vcc, v11, v10
	v_lshl_add_u64 v[6:7], s[22:23], 0, v[6:7]
	s_mov_b64 s[6:7], 0x333e8000
	v_cndmask_b32_e32 v11, v0, v11, vcc
	v_lshlrev_b32_e32 v67, 2, v11
	v_xor_b32_e32 v11, 8, v0
	v_cmp_lt_i32_e32 vcc, v11, v10
	v_lshlrev_b32_e32 v16, 2, v30
	v_mov_b32_e32 v17, v1
	v_cndmask_b32_e32 v11, v0, v11, vcc
	v_lshlrev_b32_e32 v68, 2, v11
	v_xor_b32_e32 v11, 16, v0
	v_cmp_lt_i32_e32 vcc, v11, v10
	v_lshlrev_b32_e32 v20, 2, v32
	v_mov_b32_e32 v21, v1
	v_cndmask_b32_e32 v11, v0, v11, vcc
	v_lshlrev_b32_e32 v69, 2, v11
	v_xor_b32_e32 v11, 32, v0
	v_cmp_lt_i32_e32 vcc, v11, v10
	v_lshlrev_b32_e32 v24, 2, v34
	v_mov_b32_e32 v25, v1
	v_cndmask_b32_e32 v0, v0, v11, vcc
	v_lshlrev_b32_e32 v70, 2, v0
	v_lshlrev_b32_e32 v0, 2, v28
	v_lshl_add_u64 v[6:7], v[6:7], 0, s[6:7]
	s_mov_b32 s7, 0
	v_lshl_add_u64 v[10:11], s[8:9], 0, v[0:1]
	v_lshl_add_u64 v[12:13], s[0:1], 0, v[0:1]
	v_lshl_add_u64 v[14:15], s[8:9], 0, v[16:17]
	v_lshl_add_u64 v[16:17], s[0:1], 0, v[16:17]
	v_lshl_add_u64 v[18:19], s[8:9], 0, v[20:21]
	v_lshl_add_u64 v[20:21], s[0:1], 0, v[20:21]
	v_lshl_add_u64 v[22:23], s[8:9], 0, v[24:25]
	v_lshl_add_u64 v[24:25], s[0:1], 0, v[24:25]
	v_lshl_add_u64 v[26:27], s[20:21], 0, v[0:1]
	s_mov_b64 s[8:9], 0
	s_movk_i32 s20, 0x3fff
	s_movk_i32 s21, 0x1fff
	s_movk_i32 s22, 0x6000
	s_mov_b64 s[10:11], 0x18e85000
	v_lshlrev_b32_e32 v0, 2, v28
	s_mov_b32 s12, 0x3fb504f3
	v_lshlrev_b32_e32 v28, 2, v30
	v_lshlrev_b32_e32 v30, 2, v32
	v_lshlrev_b32_e32 v32, 2, v34
	v_mov_b32_e32 v71, 0x358637bd
	s_mov_b32 s23, 0x800000
	s_waitcnt vmcnt(4)
	v_mov_b64_e32 v[72:73], v[42:43]
	s_waitcnt vmcnt(3)
	v_mov_b64_e32 v[74:75], v[40:41]
	s_waitcnt vmcnt(2)
	v_mov_b64_e32 v[76:77], v[38:39]
	s_waitcnt vmcnt(1)
	v_mov_b64_e32 v[78:79], v[36:37]
	s_waitcnt vmcnt(0)
	v_mov_b32_e32 v35, v9
	global_load_dwordx4 a[8:11], v[10:11], off
	global_load_dwordx4 a[12:15], v[12:13], off
	global_load_dwordx4 a[16:19], v[14:15], off
	global_load_dwordx4 a[20:23], v[16:17], off
	global_load_dwordx4 a[24:27], v[18:19], off
	global_load_dwordx4 a[28:31], v[20:21], off
	global_load_dwordx4 a[32:35], v[22:23], off
	global_load_dwordx4 a[36:39], v[24:25], off
	s_branch .LBB0_1651

.LBB0_1651:
	s_nop 1
	v_mbcnt_lo_u32_b32 v44, -1, 0
	v_mbcnt_hi_u32_b32 v44, -1, v44
	v_cmp_eq_u32_e32 vcc, 0, v44
	s_nop 1
	v_cndmask_b32_e64 v45, 0, 1, vcc
	v_mov_b32_e32 v44, 0x23fe0
	ds_add_rtn_u32 v34, v44, v45
	s_waitcnt lgkmcnt(0)
	v_readfirstlane_b32 s16, v34
	s_and_b32 s17, s16, 7
	s_lshr_b32 s16, s16, 3
	s_add_i32 s16, s16, 1
	s_lshl_b32 s16, s16, 11
	s_add_i32 s16, s16, s17
	s_add_i32 s16, s16, s58
	s_add_i32 s32, s32, 1
	s_cmp_gt_u32 s32, 64
	s_cselect_b32 s16, 0x4000, s16
	v_mov_b32_e32 v34, s16
	v_cmp_gt_i32_e64 s[0:1], s18, v34
	v_cmp_lt_i32_e32 vcc, s20, v34
	s_and_saveexec_b64 s[14:15], s[0:1]
	s_cbranch_execz .LBB0_1653
	v_ashrrev_i32_e32 v35, 31, v34
	v_lshlrev_b64 v[44:45], 6, v[34:35]
	v_lshl_add_u64 v[44:45], v[2:3], 0, v[44:45]
	v_lshlrev_b64 v[46:47], 11, v[34:35]
	v_lshl_add_u64 v[46:47], v[4:5], 0, v[46:47]
	global_load_dword v35, v[44:45], off
	global_load_dwordx2 v[72:73], v[46:47], off
	global_load_dwordx2 v[74:75], v[46:47], off offset:512
	global_load_dwordx2 v[76:77], v[46:47], off offset:1024
	global_load_dwordx2 v[78:79], v[46:47], off offset:1536
